# E phases: 8-byte bf16 residual stores also without nt (on top of default-policy 8-byte loads)
# baseline (speedup 1.0000x reference)
; #define GAS __attribute__((address_space(1)))
; DI unsigned pk2(float lo, float hi) { f32x2_t v = {lo, hi}; bf16x2_t b = __builtin_convertvector(v, bf16x2_t); return __builtin_bit_cast(unsigned, b); }
; DI float bflo(unsigned w) { return __uint_as_float(w << 16); }
; DI float bfhi(unsigned w) { return __uint_as_float(w & 0xffff0000u); }
; DI void phase_e(const Ctx& C, int nslab, int has_post, int pl, int ps, float pw, int has_pre, int ql, int qs, int nrows,
;                 const GAS float* xsrc, const GAS float* csrc, GAS float* xdst, GAS float* cdst, bool xs16, bool xd16) {
;     ...
;             const float r = rsqrtf(wave_sum(ss) * (1.0f / 1024.0f) + EPS);
;             if (isx && xd16) { GAS bf16* d16 = (GAS bf16*)xdst + (size_t)row * 1024;
; #pragma unroll
;                 for (int j = 0; j < 4; ++j) { v[j] += pw * gt[j] * ((y[j] * r) * gpo[j]); u32x2 w; w.x = pk2(v[j][0], v[j][1]); w.y = pk2(v[j][2], v[j][3]); __builtin_nontemporal_store(w, (GAS u32x2*)(d16 + 256 * j + 4 * lane));
;                     v[j] = (f32x4){bflo(w.x), bfhi(w.x), bflo(w.y), bfhi(w.y)}; }
.LBB0_448:
	s_andn2_b64 vcc, exec, s[22:23]
	s_cbranch_vccnz .LBB0_424_u0
	s_lshl_b64 s[2:3], s[12:13], 11
	v_mov_b32_e32 v140, v182
	v_mov_b32_e32 v141, v182
	v_lshl_add_u64 v[138:139], v[156:157], 0, s[2:3]
	v_cvt_pk_bf16_f32 v130, v126, v127
	v_cvt_pk_bf16_f32 v131, v128, v129
	v_pk_mul_f32 v[132:133], v[172:173], v[140:141]
	v_pk_mul_f32 v[134:135], v[170:171], v[182:183]
	global_store_dwordx2 v[138:139], v[130:131], off
	v_lshlrev_b32_e32 v126, 16, v130
	v_and_b32_e32 v127, 0xffff0000, v130
	v_lshlrev_b32_e32 v128, 16, v131
	v_and_b32_e32 v129, 0xffff0000, v131
	v_pk_mul_f32 v[130:131], v[100:101], 0.5 op_sel_hi:[1,0]
	v_pk_mul_f32 v[132:133], v[8:9], v[132:133]
	v_pk_mul_f32 v[134:135], v[6:7], v[134:135]
	v_pk_fma_f32 v[60:61], v[130:131], v[132:133], v[60:61]
	v_pk_fma_f32 v[58:59], v[188:189], v[134:135], v[58:59]
	v_pk_mul_f32 v[134:135], v[174:175], v[182:183]
	v_cvt_pk_bf16_f32 v58, v58, v59
	v_cvt_pk_bf16_f32 v59, v60, v61
	v_pk_mul_f32 v[60:61], v[176:177], v[140:141]
	global_store_dwordx2 v[138:139], v[58:59], off offset:512
	v_lshlrev_b32_e32 v130, 16, v58
	v_and_b32_e32 v131, 0xffff0000, v58
	v_lshlrev_b32_e32 v132, 16, v59
	v_and_b32_e32 v133, 0xffff0000, v59
	v_pk_mul_f32 v[58:59], v[104:105], 0.5 op_sel_hi:[1,0]
	v_pk_mul_f32 v[60:61], v[20:21], v[60:61]
	v_pk_mul_f32 v[134:135], v[18:19], v[134:135]
	v_pk_fma_f32 v[56:57], v[58:59], v[60:61], v[56:57]
	v_pk_fma_f32 v[54:55], v[186:187], v[134:135], v[54:55]
	v_pk_mul_f32 v[58:59], v[178:179], v[182:183]
	v_cvt_pk_bf16_f32 v54, v54, v55
	v_cvt_pk_bf16_f32 v55, v56, v57
	v_pk_mul_f32 v[56:57], v[180:181], v[140:141]
	global_store_dwordx2 v[138:139], v[54:55], off offset:1024
	v_lshlrev_b32_e32 v134, 16, v54
	v_and_b32_e32 v135, 0xffff0000, v54
	v_lshlrev_b32_e32 v136, 16, v55
	v_and_b32_e32 v137, 0xffff0000, v55
	v_pk_mul_f32 v[54:55], v[108:109], 0.5 op_sel_hi:[1,0]
	v_pk_mul_f32 v[56:57], v[24:25], v[56:57]
	v_pk_mul_f32 v[58:59], v[22:23], v[58:59]
	v_pk_fma_f32 v[52:53], v[54:55], v[56:57], v[52:53]
	v_pk_fma_f32 v[50:51], v[184:185], v[58:59], v[50:51]
	s_nop 0
	v_cvt_pk_bf16_f32 v50, v50, v51
	v_cvt_pk_bf16_f32 v51, v52, v53
	global_store_dwordx2 v[138:139], v[50:51], off offset:1536
	v_lshlrev_b32_e32 v138, 16, v50
	v_and_b32_e32 v139, 0xffff0000, v50
	v_lshlrev_b32_e32 v140, 16, v51
	v_and_b32_e32 v141, 0xffff0000, v51
	s_branch .LBB0_424_u0

; #define GAS __attribute__((address_space(1)))
; DI unsigned pk2(float lo, float hi) { f32x2_t v = {lo, hi}; bf16x2_t b = __builtin_convertvector(v, bf16x2_t); return __builtin_bit_cast(unsigned, b); }
; DI float bflo(unsigned w) { return __uint_as_float(w << 16); }
; DI float bfhi(unsigned w) { return __uint_as_float(w & 0xffff0000u); }
; DI void phase_e(const Ctx& C, int nslab, int has_post, int pl, int ps, float pw, int has_pre, int ql, int qs, int nrows,
;                 const GAS float* xsrc, const GAS float* csrc, GAS float* xdst, GAS float* cdst, bool xs16, bool xd16) {
;     ...
;             const float r = rsqrtf(wave_sum(ss) * (1.0f / 1024.0f) + EPS);
;             if (isx && xd16) { GAS bf16* d16 = (GAS bf16*)xdst + (size_t)row * 1024;
; #pragma unroll
;                 for (int j = 0; j < 4; ++j) { v[j] += pw * gt[j] * ((y[j] * r) * gpo[j]); u32x2 w; w.x = pk2(v[j][0], v[j][1]); w.y = pk2(v[j][2], v[j][3]); __builtin_nontemporal_store(w, (GAS u32x2*)(d16 + 256 * j + 4 * lane));
;                     v[j] = (f32x4){bflo(w.x), bfhi(w.x), bflo(w.y), bfhi(w.y)}; }
.Lrow1_448:
	s_andn2_b64 vcc, exec, s[22:23]
	s_cbranch_vccnz .Lrow1_424
	s_lshl_b64 s[2:3], s[12:13], 11
	v_mov_b32_e32 v140, v182
	v_mov_b32_e32 v141, v182
	v_lshl_add_u64 v[138:139], v[156:157], 0, s[2:3]
	v_cvt_pk_bf16_f32 v130, v34, v35
	v_cvt_pk_bf16_f32 v131, v36, v37
	v_pk_mul_f32 v[132:133], v[172:173], v[140:141]
	v_pk_mul_f32 v[134:135], v[170:171], v[182:183]
	global_store_dwordx2 v[138:139], v[130:131], off
	v_lshlrev_b32_e32 v34, 16, v130
	v_and_b32_e32 v35, 0xffff0000, v130
	v_lshlrev_b32_e32 v36, 16, v131
	v_and_b32_e32 v37, 0xffff0000, v131
	v_pk_mul_f32 v[130:131], v[100:101], 0.5 op_sel_hi:[1,0]
	v_pk_mul_f32 v[132:133], v[8:9], v[132:133]
	v_pk_mul_f32 v[134:135], v[6:7], v[134:135]
	v_pk_fma_f32 v[40:41], v[130:131], v[132:133], v[40:41]
	v_pk_fma_f32 v[38:39], v[188:189], v[134:135], v[38:39]
	v_pk_mul_f32 v[134:135], v[174:175], v[182:183]
	v_cvt_pk_bf16_f32 v38, v38, v39
	v_cvt_pk_bf16_f32 v39, v40, v41
	v_pk_mul_f32 v[40:41], v[176:177], v[140:141]
	global_store_dwordx2 v[138:139], v[38:39], off offset:512
	v_lshlrev_b32_e32 v130, 16, v38
	v_and_b32_e32 v131, 0xffff0000, v38
	v_lshlrev_b32_e32 v132, 16, v39
	v_and_b32_e32 v133, 0xffff0000, v39
	v_pk_mul_f32 v[38:39], v[104:105], 0.5 op_sel_hi:[1,0]
	v_pk_mul_f32 v[40:41], v[20:21], v[40:41]
	v_pk_mul_f32 v[134:135], v[18:19], v[134:135]
	v_pk_fma_f32 v[44:45], v[38:39], v[40:41], v[44:45]
	v_pk_fma_f32 v[42:43], v[186:187], v[134:135], v[42:43]
	v_pk_mul_f32 v[38:39], v[178:179], v[182:183]
	v_cvt_pk_bf16_f32 v42, v42, v43
	v_cvt_pk_bf16_f32 v43, v44, v45
	v_pk_mul_f32 v[44:45], v[180:181], v[140:141]
	global_store_dwordx2 v[138:139], v[42:43], off offset:1024
	v_lshlrev_b32_e32 v134, 16, v42
	v_and_b32_e32 v135, 0xffff0000, v42
	v_lshlrev_b32_e32 v136, 16, v43
	v_and_b32_e32 v137, 0xffff0000, v43
	v_pk_mul_f32 v[42:43], v[108:109], 0.5 op_sel_hi:[1,0]
	v_pk_mul_f32 v[44:45], v[24:25], v[44:45]
	v_pk_mul_f32 v[38:39], v[22:23], v[38:39]
	v_pk_fma_f32 v[48:49], v[42:43], v[44:45], v[48:49]
	v_pk_fma_f32 v[46:47], v[184:185], v[38:39], v[46:47]
	s_nop 0
	v_cvt_pk_bf16_f32 v46, v46, v47
	v_cvt_pk_bf16_f32 v47, v48, v49
	global_store_dwordx2 v[138:139], v[46:47], off offset:1536
	v_lshlrev_b32_e32 v138, 16, v46
	v_and_b32_e32 v139, 0xffff0000, v46
	v_lshlrev_b32_e32 v140, 16, v47
	v_and_b32_e32 v141, 0xffff0000, v47
	s_branch .Lrow1_424

; #define GAS __attribute__((address_space(1)))
; DI unsigned pk2(float lo, float hi) { f32x2_t v = {lo, hi}; bf16x2_t b = __builtin_convertvector(v, bf16x2_t); return __builtin_bit_cast(unsigned, b); }
; DI float bflo(unsigned w) { return __uint_as_float(w << 16); }
; DI float bfhi(unsigned w) { return __uint_as_float(w & 0xffff0000u); }
; DI void phase_e(const Ctx& C, int nslab, int has_post, int pl, int ps, float pw, int has_pre, int ql, int qs, int nrows,
;                 const GAS float* xsrc, const GAS float* csrc, GAS float* xdst, GAS float* cdst, bool xs16, bool xd16) {
;     ...
;             const float r = rsqrtf(wave_sum(ss) * (1.0f / 1024.0f) + EPS);
;             if (isx && xd16) { GAS bf16* d16 = (GAS bf16*)xdst + (size_t)row * 1024;
; #pragma unroll
;                 for (int j = 0; j < 4; ++j) { v[j] += pw * gt[j] * ((y[j] * r) * gpo[j]); u32x2 w; w.x = pk2(v[j][0], v[j][1]); w.y = pk2(v[j][2], v[j][3]); __builtin_nontemporal_store(w, (GAS u32x2*)(d16 + 256 * j + 4 * lane));
;                     v[j] = (f32x4){bflo(w.x), bfhi(w.x), bflo(w.y), bfhi(w.y)}; }
.Lrow2_448:
	s_andn2_b64 vcc, exec, s[22:23]
	s_cbranch_vccnz .LBB0_424
	s_lshl_b64 s[2:3], s[12:13], 11
	v_mov_b32_e32 v140, v182
	v_mov_b32_e32 v141, v182
	v_lshl_add_u64 v[138:139], v[156:157], 0, s[2:3]
	v_cvt_pk_bf16_f32 v130, v122, v123
	v_cvt_pk_bf16_f32 v131, v124, v125
	v_pk_mul_f32 v[132:133], v[172:173], v[140:141]
	v_pk_mul_f32 v[134:135], v[170:171], v[182:183]
	global_store_dwordx2 v[138:139], v[130:131], off
	v_lshlrev_b32_e32 v122, 16, v130
	v_and_b32_e32 v123, 0xffff0000, v130
	v_lshlrev_b32_e32 v124, 16, v131
	v_and_b32_e32 v125, 0xffff0000, v131
	v_pk_mul_f32 v[130:131], v[100:101], 0.5 op_sel_hi:[1,0]
	v_pk_mul_f32 v[132:133], v[8:9], v[132:133]
	v_pk_mul_f32 v[134:135], v[6:7], v[134:135]
	v_pk_fma_f32 v[120:121], v[130:131], v[132:133], v[120:121]
	v_pk_fma_f32 v[118:119], v[188:189], v[134:135], v[118:119]
	v_pk_mul_f32 v[134:135], v[174:175], v[182:183]
	v_cvt_pk_bf16_f32 v118, v118, v119
	v_cvt_pk_bf16_f32 v119, v120, v121
	v_pk_mul_f32 v[120:121], v[176:177], v[140:141]
	global_store_dwordx2 v[138:139], v[118:119], off offset:512
	v_lshlrev_b32_e32 v130, 16, v118
	v_and_b32_e32 v131, 0xffff0000, v118
	v_lshlrev_b32_e32 v132, 16, v119
	v_and_b32_e32 v133, 0xffff0000, v119
	v_pk_mul_f32 v[118:119], v[104:105], 0.5 op_sel_hi:[1,0]
	v_pk_mul_f32 v[120:121], v[20:21], v[120:121]
	v_pk_mul_f32 v[134:135], v[18:19], v[134:135]
	v_pk_fma_f32 v[116:117], v[118:119], v[120:121], v[116:117]
	v_pk_fma_f32 v[114:115], v[186:187], v[134:135], v[114:115]
	v_pk_mul_f32 v[118:119], v[178:179], v[182:183]
	v_cvt_pk_bf16_f32 v114, v114, v115
	v_cvt_pk_bf16_f32 v115, v116, v117
	v_pk_mul_f32 v[116:117], v[180:181], v[140:141]
	global_store_dwordx2 v[138:139], v[114:115], off offset:1024
	v_lshlrev_b32_e32 v134, 16, v114
	v_and_b32_e32 v135, 0xffff0000, v114
	v_lshlrev_b32_e32 v136, 16, v115
	v_and_b32_e32 v137, 0xffff0000, v115
	v_pk_mul_f32 v[114:115], v[108:109], 0.5 op_sel_hi:[1,0]
	v_pk_mul_f32 v[116:117], v[24:25], v[116:117]
	v_pk_mul_f32 v[118:119], v[22:23], v[118:119]
	v_pk_fma_f32 v[112:113], v[114:115], v[116:117], v[112:113]
	v_pk_fma_f32 v[110:111], v[184:185], v[118:119], v[110:111]
	s_nop 0
	v_cvt_pk_bf16_f32 v110, v110, v111
	v_cvt_pk_bf16_f32 v111, v112, v113
	global_store_dwordx2 v[138:139], v[110:111], off offset:1536
	v_lshlrev_b32_e32 v138, 16, v110
	v_and_b32_e32 v139, 0xffff0000, v110
	v_lshlrev_b32_e32 v140, 16, v111
	v_and_b32_e32 v141, 0xffff0000, v111
	s_branch .LBB0_424

; #define GAS __attribute__((address_space(1)))
; DI unsigned pk2(float lo, float hi) { f32x2_t v = {lo, hi}; bf16x2_t b = __builtin_convertvector(v, bf16x2_t); return __builtin_bit_cast(unsigned, b); }
; DI float bflo(unsigned w) { return __uint_as_float(w << 16); }
; DI float bfhi(unsigned w) { return __uint_as_float(w & 0xffff0000u); }
; DI void phase_e(const Ctx& C, int nslab, int has_post, int pl, int ps, float pw, int has_pre, int ql, int qs, int nrows,
;                 const GAS float* xsrc, const GAS float* csrc, GAS float* xdst, GAS float* cdst, bool xs16, bool xd16) {
;     ...
;             const float r = rsqrtf(wave_sum(ss) * (1.0f / 1024.0f) + EPS);
;             if (isx && xd16) { GAS bf16* d16 = (GAS bf16*)xdst + (size_t)row * 1024;
; #pragma unroll
;                 for (int j = 0; j < 4; ++j) { v[j] += pw * gt[j] * ((y[j] * r) * gpo[j]); u32x2 w; w.x = pk2(v[j][0], v[j][1]); w.y = pk2(v[j][2], v[j][3]); __builtin_nontemporal_store(w, (GAS u32x2*)(d16 + 256 * j + 4 * lane));
;                     v[j] = (f32x4){bflo(w.x), bfhi(w.x), bflo(w.y), bfhi(w.y)}; }
.LBB0_973:
	s_andn2_b64 vcc, exec, s[12:13]
	s_cbranch_vccnz .LBB0_945_u0
	s_lshl_b64 s[2:3], s[10:11], 11
	v_lshl_add_u64 v[138:139], v[152:153], 0, s[2:3]
	v_cvt_pk_bf16_f32 v130, v78, v79
	v_cvt_pk_bf16_f32 v131, v80, v81
	v_mov_b32_e32 v140, v184
	v_mov_b32_e32 v141, v184
	global_store_dwordx2 v[138:139], v[130:131], off
	v_lshlrev_b32_e32 v78, 16, v130
	v_and_b32_e32 v79, 0xffff0000, v130
	v_lshlrev_b32_e32 v80, 16, v131
	v_and_b32_e32 v81, 0xffff0000, v131
	v_pk_mul_f32 v[130:131], v[172:173], v[140:141]
	v_pk_mul_f32 v[132:133], v[170:171], v[184:185]
	v_pk_mul_f32 v[130:131], v[8:9], v[130:131]
	v_pk_mul_f32 v[132:133], v[6:7], v[132:133]
	s_waitcnt vmcnt(8)
	v_pk_fma_f32 v[60:61], v[104:105], v[130:131], v[60:61]
	v_pk_fma_f32 v[58:59], v[102:103], v[132:133], v[58:59]
	s_nop 0
	v_cvt_pk_bf16_f32 v58, v58, v59
	v_cvt_pk_bf16_f32 v59, v60, v61
	global_store_dwordx2 v[138:139], v[58:59], off offset:512
	v_lshlrev_b32_e32 v130, 16, v58
	v_and_b32_e32 v131, 0xffff0000, v58
	v_lshlrev_b32_e32 v132, 16, v59
	v_and_b32_e32 v133, 0xffff0000, v59
	v_pk_mul_f32 v[58:59], v[178:179], v[140:141]
	v_pk_mul_f32 v[60:61], v[176:177], v[184:185]
	v_pk_mul_f32 v[58:59], v[20:21], v[58:59]
	v_pk_mul_f32 v[60:61], v[18:19], v[60:61]
	s_waitcnt vmcnt(8)
	v_pk_fma_f32 v[56:57], v[108:109], v[58:59], v[56:57]
	v_pk_fma_f32 v[54:55], v[106:107], v[60:61], v[54:55]
	s_nop 0
	v_cvt_pk_bf16_f32 v54, v54, v55
	v_cvt_pk_bf16_f32 v55, v56, v57
	global_store_dwordx2 v[138:139], v[54:55], off offset:1024
	v_lshlrev_b32_e32 v134, 16, v54
	v_and_b32_e32 v135, 0xffff0000, v54
	v_lshlrev_b32_e32 v136, 16, v55
	v_and_b32_e32 v137, 0xffff0000, v55
	v_pk_mul_f32 v[54:55], v[182:183], v[140:141]
	v_pk_mul_f32 v[56:57], v[180:181], v[184:185]
	v_pk_mul_f32 v[54:55], v[24:25], v[54:55]
	v_pk_mul_f32 v[56:57], v[22:23], v[56:57]
	s_waitcnt vmcnt(7)
	v_pk_fma_f32 v[48:49], v[112:113], v[54:55], v[48:49]
	v_pk_fma_f32 v[46:47], v[110:111], v[56:57], v[46:47]
	s_nop 0
	v_cvt_pk_bf16_f32 v46, v46, v47
	v_cvt_pk_bf16_f32 v47, v48, v49
	global_store_dwordx2 v[138:139], v[46:47], off offset:1536
	v_lshlrev_b32_e32 v138, 16, v46
	v_and_b32_e32 v139, 0xffff0000, v46
	v_lshlrev_b32_e32 v140, 16, v47
	v_and_b32_e32 v141, 0xffff0000, v47
	s_branch .LBB0_945_u0

; #define GAS __attribute__((address_space(1)))
; DI unsigned pk2(float lo, float hi) { f32x2_t v = {lo, hi}; bf16x2_t b = __builtin_convertvector(v, bf16x2_t); return __builtin_bit_cast(unsigned, b); }
; DI float bflo(unsigned w) { return __uint_as_float(w << 16); }
; DI float bfhi(unsigned w) { return __uint_as_float(w & 0xffff0000u); }
; DI void phase_e(const Ctx& C, int nslab, int has_post, int pl, int ps, float pw, int has_pre, int ql, int qs, int nrows,
;                 const GAS float* xsrc, const GAS float* csrc, GAS float* xdst, GAS float* cdst, bool xs16, bool xd16) {
;     ...
;             const float r = rsqrtf(wave_sum(ss) * (1.0f / 1024.0f) + EPS);
;             if (isx && xd16) { GAS bf16* d16 = (GAS bf16*)xdst + (size_t)row * 1024;
; #pragma unroll
;                 for (int j = 0; j < 4; ++j) { v[j] += pw * gt[j] * ((y[j] * r) * gpo[j]); u32x2 w; w.x = pk2(v[j][0], v[j][1]); w.y = pk2(v[j][2], v[j][3]); __builtin_nontemporal_store(w, (GAS u32x2*)(d16 + 256 * j + 4 * lane));
;                     v[j] = (f32x4){bflo(w.x), bfhi(w.x), bflo(w.y), bfhi(w.y)}; }
.Lrow1_973:
	s_andn2_b64 vcc, exec, s[12:13]
	s_cbranch_vccnz .Lrow1_945
	s_lshl_b64 s[2:3], s[10:11], 11
	v_lshl_add_u64 v[138:139], v[152:153], 0, s[2:3]
	v_cvt_pk_bf16_f32 v130, v34, v35
	v_cvt_pk_bf16_f32 v131, v36, v37
	v_mov_b32_e32 v140, v184
	v_mov_b32_e32 v141, v184
	global_store_dwordx2 v[138:139], v[130:131], off
	v_lshlrev_b32_e32 v34, 16, v130
	v_and_b32_e32 v35, 0xffff0000, v130
	v_lshlrev_b32_e32 v36, 16, v131
	v_and_b32_e32 v37, 0xffff0000, v131
	v_pk_mul_f32 v[130:131], v[172:173], v[140:141]
	v_pk_mul_f32 v[132:133], v[170:171], v[184:185]
	v_pk_mul_f32 v[130:131], v[8:9], v[130:131]
	v_pk_mul_f32 v[132:133], v[6:7], v[132:133]
	s_waitcnt vmcnt(8)
	v_pk_fma_f32 v[40:41], v[104:105], v[130:131], v[40:41]
	v_pk_fma_f32 v[38:39], v[102:103], v[132:133], v[38:39]
	s_nop 0
	v_cvt_pk_bf16_f32 v38, v38, v39
	v_cvt_pk_bf16_f32 v39, v40, v41
	global_store_dwordx2 v[138:139], v[38:39], off offset:512
	v_lshlrev_b32_e32 v130, 16, v38
	v_and_b32_e32 v131, 0xffff0000, v38
	v_lshlrev_b32_e32 v132, 16, v39
	v_and_b32_e32 v133, 0xffff0000, v39
	v_pk_mul_f32 v[38:39], v[178:179], v[140:141]
	v_pk_mul_f32 v[40:41], v[176:177], v[184:185]
	v_pk_mul_f32 v[38:39], v[20:21], v[38:39]
	v_pk_mul_f32 v[40:41], v[18:19], v[40:41]
	s_waitcnt vmcnt(8)
	v_pk_fma_f32 v[44:45], v[108:109], v[38:39], v[44:45]
	v_pk_fma_f32 v[42:43], v[106:107], v[40:41], v[42:43]
	s_nop 0
	v_cvt_pk_bf16_f32 v42, v42, v43
	v_cvt_pk_bf16_f32 v43, v44, v45
	global_store_dwordx2 v[138:139], v[42:43], off offset:1024
	v_lshlrev_b32_e32 v134, 16, v42
	v_and_b32_e32 v135, 0xffff0000, v42
	v_lshlrev_b32_e32 v136, 16, v43
	v_and_b32_e32 v137, 0xffff0000, v43
	v_pk_mul_f32 v[42:43], v[182:183], v[140:141]
	v_pk_mul_f32 v[44:45], v[180:181], v[184:185]
	v_pk_mul_f32 v[42:43], v[24:25], v[42:43]
	v_pk_mul_f32 v[44:45], v[22:23], v[44:45]
	s_waitcnt vmcnt(7)
	v_pk_fma_f32 v[52:53], v[112:113], v[42:43], v[52:53]
	v_pk_fma_f32 v[50:51], v[110:111], v[44:45], v[50:51]
	s_nop 0
	v_cvt_pk_bf16_f32 v50, v50, v51
	v_cvt_pk_bf16_f32 v51, v52, v53
	global_store_dwordx2 v[138:139], v[50:51], off offset:1536
	v_lshlrev_b32_e32 v138, 16, v50
	v_and_b32_e32 v139, 0xffff0000, v50
	v_lshlrev_b32_e32 v140, 16, v51
	v_and_b32_e32 v141, 0xffff0000, v51
	s_branch .Lrow1_945

; #define GAS __attribute__((address_space(1)))
; DI unsigned pk2(float lo, float hi) { f32x2_t v = {lo, hi}; bf16x2_t b = __builtin_convertvector(v, bf16x2_t); return __builtin_bit_cast(unsigned, b); }
; DI float bflo(unsigned w) { return __uint_as_float(w << 16); }
; DI float bfhi(unsigned w) { return __uint_as_float(w & 0xffff0000u); }
; DI void phase_e(const Ctx& C, int nslab, int has_post, int pl, int ps, float pw, int has_pre, int ql, int qs, int nrows,
;                 const GAS float* xsrc, const GAS float* csrc, GAS float* xdst, GAS float* cdst, bool xs16, bool xd16) {
;     ...
;             const float r = rsqrtf(wave_sum(ss) * (1.0f / 1024.0f) + EPS);
;             if (isx && xd16) { GAS bf16* d16 = (GAS bf16*)xdst + (size_t)row * 1024;
; #pragma unroll
;                 for (int j = 0; j < 4; ++j) { v[j] += pw * gt[j] * ((y[j] * r) * gpo[j]); u32x2 w; w.x = pk2(v[j][0], v[j][1]); w.y = pk2(v[j][2], v[j][3]); __builtin_nontemporal_store(w, (GAS u32x2*)(d16 + 256 * j + 4 * lane));
;                     v[j] = (f32x4){bflo(w.x), bfhi(w.x), bflo(w.y), bfhi(w.y)}; }
.Lrow2_973:
	s_andn2_b64 vcc, exec, s[12:13]
	s_cbranch_vccnz .LBB0_945
	s_lshl_b64 s[2:3], s[10:11], 11
	v_lshl_add_u64 v[138:139], v[152:153], 0, s[2:3]
	v_cvt_pk_bf16_f32 v130, v114, v115
	v_cvt_pk_bf16_f32 v131, v116, v117
	v_mov_b32_e32 v140, v184
	v_mov_b32_e32 v141, v184
	global_store_dwordx2 v[138:139], v[130:131], off
	v_lshlrev_b32_e32 v114, 16, v130
	v_and_b32_e32 v115, 0xffff0000, v130
	v_lshlrev_b32_e32 v116, 16, v131
	v_and_b32_e32 v117, 0xffff0000, v131
	v_pk_mul_f32 v[130:131], v[172:173], v[140:141]
	v_pk_mul_f32 v[132:133], v[170:171], v[184:185]
	v_pk_mul_f32 v[130:131], v[8:9], v[130:131]
	v_pk_mul_f32 v[132:133], v[6:7], v[132:133]
	s_waitcnt vmcnt(8)
	v_pk_fma_f32 v[120:121], v[104:105], v[130:131], v[120:121]
	v_pk_fma_f32 v[118:119], v[102:103], v[132:133], v[118:119]
	s_nop 0
	v_cvt_pk_bf16_f32 v118, v118, v119
	v_cvt_pk_bf16_f32 v119, v120, v121
	global_store_dwordx2 v[138:139], v[118:119], off offset:512
	v_lshlrev_b32_e32 v130, 16, v118
	v_and_b32_e32 v131, 0xffff0000, v118
	v_lshlrev_b32_e32 v132, 16, v119
	v_and_b32_e32 v133, 0xffff0000, v119
	v_pk_mul_f32 v[118:119], v[178:179], v[140:141]
	v_pk_mul_f32 v[120:121], v[176:177], v[184:185]
	v_pk_mul_f32 v[118:119], v[20:21], v[118:119]
	v_pk_mul_f32 v[120:121], v[18:19], v[120:121]
	s_waitcnt vmcnt(8)
	v_pk_fma_f32 v[124:125], v[108:109], v[118:119], v[124:125]
	v_pk_fma_f32 v[122:123], v[106:107], v[120:121], v[122:123]
	s_nop 0
	v_cvt_pk_bf16_f32 v122, v122, v123
	v_cvt_pk_bf16_f32 v123, v124, v125
	global_store_dwordx2 v[138:139], v[122:123], off offset:1024
	v_lshlrev_b32_e32 v134, 16, v122
	v_and_b32_e32 v135, 0xffff0000, v122
	v_lshlrev_b32_e32 v136, 16, v123
	v_and_b32_e32 v137, 0xffff0000, v123
	v_pk_mul_f32 v[122:123], v[182:183], v[140:141]
	v_pk_mul_f32 v[124:125], v[180:181], v[184:185]
	v_pk_mul_f32 v[122:123], v[24:25], v[122:123]
	v_pk_mul_f32 v[124:125], v[22:23], v[124:125]
	s_waitcnt vmcnt(7)
	v_pk_fma_f32 v[128:129], v[112:113], v[122:123], v[128:129]
	v_pk_fma_f32 v[126:127], v[110:111], v[124:125], v[126:127]
	s_nop 0
	v_cvt_pk_bf16_f32 v126, v126, v127
	v_cvt_pk_bf16_f32 v127, v128, v129
	global_store_dwordx2 v[138:139], v[126:127], off offset:1536
	v_lshlrev_b32_e32 v138, 16, v126
	v_and_b32_e32 v139, 0xffff0000, v126
	v_lshlrev_b32_e32 v140, 16, v127
	v_and_b32_e32 v141, 0xffff0000, v127
	s_branch .LBB0_945

; #define GAS __attribute__((address_space(1)))
; DI unsigned pk2(float lo, float hi) { f32x2_t v = {lo, hi}; bf16x2_t b = __builtin_convertvector(v, bf16x2_t); return __builtin_bit_cast(unsigned, b); }
; DI float bflo(unsigned w) { return __uint_as_float(w << 16); }
; DI float bfhi(unsigned w) { return __uint_as_float(w & 0xffff0000u); }
; DI void phase_e(const Ctx& C, int nslab, int has_post, int pl, int ps, float pw, int has_pre, int ql, int qs, int nrows,
;                 const GAS float* xsrc, const GAS float* csrc, GAS float* xdst, GAS float* cdst, bool xs16, bool xd16) {
;     ...
;             const float r = rsqrtf(wave_sum(ss) * (1.0f / 1024.0f) + EPS);
;             if (isx && xd16) { GAS bf16* d16 = (GAS bf16*)xdst + (size_t)row * 1024;
; #pragma unroll
;                 for (int j = 0; j < 4; ++j) { v[j] += pw * gt[j] * ((y[j] * r) * gpo[j]); u32x2 w; w.x = pk2(v[j][0], v[j][1]); w.y = pk2(v[j][2], v[j][3]); __builtin_nontemporal_store(w, (GAS u32x2*)(d16 + 256 * j + 4 * lane));
;                     v[j] = (f32x4){bflo(w.x), bfhi(w.x), bflo(w.y), bfhi(w.y)}; }
.LBB0_1240:
	s_andn2_b64 vcc, exec, s[12:13]
	s_cbranch_vccnz .LBB0_1212_u0
	s_lshl_b64 s[2:3], s[10:11], 11
	v_mov_b32_e32 v140, v182
	v_mov_b32_e32 v141, v182
	v_lshl_add_u64 v[138:139], v[152:153], 0, s[2:3]
	v_cvt_pk_bf16_f32 v130, v98, v99
	v_cvt_pk_bf16_f32 v131, v100, v101
	v_pk_mul_f32 v[132:133], v[172:173], v[140:141]
	v_pk_mul_f32 v[134:135], v[170:171], v[182:183]
	global_store_dwordx2 v[138:139], v[130:131], off
	v_lshlrev_b32_e32 v98, 16, v130
	v_and_b32_e32 v99, 0xffff0000, v130
	v_lshlrev_b32_e32 v100, 16, v131
	v_and_b32_e32 v101, 0xffff0000, v131
	v_pk_mul_f32 v[130:131], v[104:105], 0.5 op_sel_hi:[1,0]
	v_pk_mul_f32 v[132:133], v[8:9], v[132:133]
	v_pk_mul_f32 v[134:135], v[6:7], v[134:135]
	v_pk_fma_f32 v[60:61], v[130:131], v[132:133], v[60:61]
	v_pk_fma_f32 v[58:59], v[188:189], v[134:135], v[58:59]
	v_pk_mul_f32 v[134:135], v[174:175], v[182:183]
	v_cvt_pk_bf16_f32 v58, v58, v59
	v_cvt_pk_bf16_f32 v59, v60, v61
	v_pk_mul_f32 v[60:61], v[176:177], v[140:141]
	global_store_dwordx2 v[138:139], v[58:59], off offset:512
	v_lshlrev_b32_e32 v130, 16, v58
	v_and_b32_e32 v131, 0xffff0000, v58
	v_lshlrev_b32_e32 v132, 16, v59
	v_and_b32_e32 v133, 0xffff0000, v59
	v_pk_mul_f32 v[58:59], v[108:109], 0.5 op_sel_hi:[1,0]
	v_pk_mul_f32 v[60:61], v[20:21], v[60:61]
	v_pk_mul_f32 v[134:135], v[18:19], v[134:135]
	v_pk_fma_f32 v[56:57], v[58:59], v[60:61], v[56:57]
	v_pk_fma_f32 v[54:55], v[186:187], v[134:135], v[54:55]
	v_pk_mul_f32 v[58:59], v[178:179], v[182:183]
	v_cvt_pk_bf16_f32 v54, v54, v55
	v_cvt_pk_bf16_f32 v55, v56, v57
	v_pk_mul_f32 v[56:57], v[180:181], v[140:141]
	global_store_dwordx2 v[138:139], v[54:55], off offset:1024
	v_lshlrev_b32_e32 v134, 16, v54
	v_and_b32_e32 v135, 0xffff0000, v54
	v_lshlrev_b32_e32 v136, 16, v55
	v_and_b32_e32 v137, 0xffff0000, v55
	v_pk_mul_f32 v[54:55], v[112:113], 0.5 op_sel_hi:[1,0]
	v_pk_mul_f32 v[56:57], v[24:25], v[56:57]
	v_pk_mul_f32 v[58:59], v[22:23], v[58:59]
	v_pk_fma_f32 v[48:49], v[54:55], v[56:57], v[48:49]
	v_pk_fma_f32 v[46:47], v[184:185], v[58:59], v[46:47]
	s_nop 0
	v_cvt_pk_bf16_f32 v46, v46, v47
	v_cvt_pk_bf16_f32 v47, v48, v49
	global_store_dwordx2 v[138:139], v[46:47], off offset:1536
	v_lshlrev_b32_e32 v138, 16, v46
	v_and_b32_e32 v139, 0xffff0000, v46
	v_lshlrev_b32_e32 v140, 16, v47
	v_and_b32_e32 v141, 0xffff0000, v47
	s_branch .LBB0_1212_u0

; #define GAS __attribute__((address_space(1)))
; DI unsigned pk2(float lo, float hi) { f32x2_t v = {lo, hi}; bf16x2_t b = __builtin_convertvector(v, bf16x2_t); return __builtin_bit_cast(unsigned, b); }
; DI float bflo(unsigned w) { return __uint_as_float(w << 16); }
; DI float bfhi(unsigned w) { return __uint_as_float(w & 0xffff0000u); }
; DI void phase_e(const Ctx& C, int nslab, int has_post, int pl, int ps, float pw, int has_pre, int ql, int qs, int nrows,
;                 const GAS float* xsrc, const GAS float* csrc, GAS float* xdst, GAS float* cdst, bool xs16, bool xd16) {
;     ...
;             const float r = rsqrtf(wave_sum(ss) * (1.0f / 1024.0f) + EPS);
;             if (isx && xd16) { GAS bf16* d16 = (GAS bf16*)xdst + (size_t)row * 1024;
; #pragma unroll
;                 for (int j = 0; j < 4; ++j) { v[j] += pw * gt[j] * ((y[j] * r) * gpo[j]); u32x2 w; w.x = pk2(v[j][0], v[j][1]); w.y = pk2(v[j][2], v[j][3]); __builtin_nontemporal_store(w, (GAS u32x2*)(d16 + 256 * j + 4 * lane));
;                     v[j] = (f32x4){bflo(w.x), bfhi(w.x), bflo(w.y), bfhi(w.y)}; }
.Lrow1_1240:
	s_andn2_b64 vcc, exec, s[12:13]
	s_cbranch_vccnz .Lrow1_1212
	s_lshl_b64 s[2:3], s[10:11], 11
	v_mov_b32_e32 v140, v182
	v_mov_b32_e32 v141, v182
	v_lshl_add_u64 v[138:139], v[152:153], 0, s[2:3]
	v_cvt_pk_bf16_f32 v130, v34, v35
	v_cvt_pk_bf16_f32 v131, v36, v37
	v_pk_mul_f32 v[132:133], v[172:173], v[140:141]
	v_pk_mul_f32 v[134:135], v[170:171], v[182:183]
	global_store_dwordx2 v[138:139], v[130:131], off
	v_lshlrev_b32_e32 v34, 16, v130
	v_and_b32_e32 v35, 0xffff0000, v130
	v_lshlrev_b32_e32 v36, 16, v131
	v_and_b32_e32 v37, 0xffff0000, v131
	v_pk_mul_f32 v[130:131], v[104:105], 0.5 op_sel_hi:[1,0]
	v_pk_mul_f32 v[132:133], v[8:9], v[132:133]
	v_pk_mul_f32 v[134:135], v[6:7], v[134:135]
	v_pk_fma_f32 v[40:41], v[130:131], v[132:133], v[40:41]
	v_pk_fma_f32 v[38:39], v[188:189], v[134:135], v[38:39]
	v_pk_mul_f32 v[134:135], v[174:175], v[182:183]
	v_cvt_pk_bf16_f32 v38, v38, v39
	v_cvt_pk_bf16_f32 v39, v40, v41
	v_pk_mul_f32 v[40:41], v[176:177], v[140:141]
	global_store_dwordx2 v[138:139], v[38:39], off offset:512
	v_lshlrev_b32_e32 v130, 16, v38
	v_and_b32_e32 v131, 0xffff0000, v38
	v_lshlrev_b32_e32 v132, 16, v39
	v_and_b32_e32 v133, 0xffff0000, v39
	v_pk_mul_f32 v[38:39], v[108:109], 0.5 op_sel_hi:[1,0]
	v_pk_mul_f32 v[40:41], v[20:21], v[40:41]
	v_pk_mul_f32 v[134:135], v[18:19], v[134:135]
	v_pk_fma_f32 v[44:45], v[38:39], v[40:41], v[44:45]
	v_pk_fma_f32 v[42:43], v[186:187], v[134:135], v[42:43]
	v_pk_mul_f32 v[38:39], v[178:179], v[182:183]
	v_cvt_pk_bf16_f32 v42, v42, v43
	v_cvt_pk_bf16_f32 v43, v44, v45
	v_pk_mul_f32 v[44:45], v[180:181], v[140:141]
	global_store_dwordx2 v[138:139], v[42:43], off offset:1024
	v_lshlrev_b32_e32 v134, 16, v42
	v_and_b32_e32 v135, 0xffff0000, v42
	v_lshlrev_b32_e32 v136, 16, v43
	v_and_b32_e32 v137, 0xffff0000, v43
	v_pk_mul_f32 v[42:43], v[112:113], 0.5 op_sel_hi:[1,0]
	v_pk_mul_f32 v[44:45], v[24:25], v[44:45]
	v_pk_mul_f32 v[38:39], v[22:23], v[38:39]
	v_pk_fma_f32 v[52:53], v[42:43], v[44:45], v[52:53]
	v_pk_fma_f32 v[50:51], v[184:185], v[38:39], v[50:51]
	s_nop 0
	v_cvt_pk_bf16_f32 v50, v50, v51
	v_cvt_pk_bf16_f32 v51, v52, v53
	global_store_dwordx2 v[138:139], v[50:51], off offset:1536
	v_lshlrev_b32_e32 v138, 16, v50
	v_and_b32_e32 v139, 0xffff0000, v50
	v_lshlrev_b32_e32 v140, 16, v51
	v_and_b32_e32 v141, 0xffff0000, v51
	s_branch .Lrow1_1212

; #define GAS __attribute__((address_space(1)))
; DI unsigned pk2(float lo, float hi) { f32x2_t v = {lo, hi}; bf16x2_t b = __builtin_convertvector(v, bf16x2_t); return __builtin_bit_cast(unsigned, b); }
; DI float bflo(unsigned w) { return __uint_as_float(w << 16); }
; DI float bfhi(unsigned w) { return __uint_as_float(w & 0xffff0000u); }
; DI void phase_e(const Ctx& C, int nslab, int has_post, int pl, int ps, float pw, int has_pre, int ql, int qs, int nrows,
;                 const GAS float* xsrc, const GAS float* csrc, GAS float* xdst, GAS float* cdst, bool xs16, bool xd16) {
;     ...
;             const float r = rsqrtf(wave_sum(ss) * (1.0f / 1024.0f) + EPS);
;             if (isx && xd16) { GAS bf16* d16 = (GAS bf16*)xdst + (size_t)row * 1024;
; #pragma unroll
;                 for (int j = 0; j < 4; ++j) { v[j] += pw * gt[j] * ((y[j] * r) * gpo[j]); u32x2 w; w.x = pk2(v[j][0], v[j][1]); w.y = pk2(v[j][2], v[j][3]); __builtin_nontemporal_store(w, (GAS u32x2*)(d16 + 256 * j + 4 * lane));
;                     v[j] = (f32x4){bflo(w.x), bfhi(w.x), bflo(w.y), bfhi(w.y)}; }
.Lrow2_1240:
	s_andn2_b64 vcc, exec, s[12:13]
	s_cbranch_vccnz .LBB0_1212
	s_lshl_b64 s[2:3], s[10:11], 11
	v_mov_b32_e32 v140, v182
	v_mov_b32_e32 v141, v182
	v_lshl_add_u64 v[138:139], v[152:153], 0, s[2:3]
	v_cvt_pk_bf16_f32 v130, v114, v115
	v_cvt_pk_bf16_f32 v131, v116, v117
	v_pk_mul_f32 v[132:133], v[172:173], v[140:141]
	v_pk_mul_f32 v[134:135], v[170:171], v[182:183]
	global_store_dwordx2 v[138:139], v[130:131], off
	v_lshlrev_b32_e32 v114, 16, v130
	v_and_b32_e32 v115, 0xffff0000, v130
	v_lshlrev_b32_e32 v116, 16, v131
	v_and_b32_e32 v117, 0xffff0000, v131
	v_pk_mul_f32 v[130:131], v[104:105], 0.5 op_sel_hi:[1,0]
	v_pk_mul_f32 v[132:133], v[8:9], v[132:133]
	v_pk_mul_f32 v[134:135], v[6:7], v[134:135]
	v_pk_fma_f32 v[120:121], v[130:131], v[132:133], v[120:121]
	v_pk_fma_f32 v[118:119], v[188:189], v[134:135], v[118:119]
	v_pk_mul_f32 v[134:135], v[174:175], v[182:183]
	v_cvt_pk_bf16_f32 v118, v118, v119
	v_cvt_pk_bf16_f32 v119, v120, v121
	v_pk_mul_f32 v[120:121], v[176:177], v[140:141]
	global_store_dwordx2 v[138:139], v[118:119], off offset:512
	v_lshlrev_b32_e32 v130, 16, v118
	v_and_b32_e32 v131, 0xffff0000, v118
	v_lshlrev_b32_e32 v132, 16, v119
	v_and_b32_e32 v133, 0xffff0000, v119
	v_pk_mul_f32 v[118:119], v[108:109], 0.5 op_sel_hi:[1,0]
	v_pk_mul_f32 v[120:121], v[20:21], v[120:121]
	v_pk_mul_f32 v[134:135], v[18:19], v[134:135]
	v_pk_fma_f32 v[124:125], v[118:119], v[120:121], v[124:125]
	v_pk_fma_f32 v[122:123], v[186:187], v[134:135], v[122:123]
	v_pk_mul_f32 v[118:119], v[178:179], v[182:183]
	v_cvt_pk_bf16_f32 v122, v122, v123
	v_cvt_pk_bf16_f32 v123, v124, v125
	v_pk_mul_f32 v[124:125], v[180:181], v[140:141]
	global_store_dwordx2 v[138:139], v[122:123], off offset:1024
	v_lshlrev_b32_e32 v134, 16, v122
	v_and_b32_e32 v135, 0xffff0000, v122
	v_lshlrev_b32_e32 v136, 16, v123
	v_and_b32_e32 v137, 0xffff0000, v123
	v_pk_mul_f32 v[122:123], v[112:113], 0.5 op_sel_hi:[1,0]
	v_pk_mul_f32 v[124:125], v[24:25], v[124:125]
	v_pk_mul_f32 v[118:119], v[22:23], v[118:119]
	v_pk_fma_f32 v[128:129], v[122:123], v[124:125], v[128:129]
	v_pk_fma_f32 v[126:127], v[184:185], v[118:119], v[126:127]
	s_nop 0
	v_cvt_pk_bf16_f32 v126, v126, v127
	v_cvt_pk_bf16_f32 v127, v128, v129
	global_store_dwordx2 v[138:139], v[126:127], off offset:1536
	v_lshlrev_b32_e32 v138, 16, v126
	v_and_b32_e32 v139, 0xffff0000, v126
	v_lshlrev_b32_e32 v140, 16, v127
	v_and_b32_e32 v141, 0xffff0000, v127
	s_branch .LBB0_1212

; #define GAS __attribute__((address_space(1)))
; DI unsigned pk2(float lo, float hi) { f32x2_t v = {lo, hi}; bf16x2_t b = __builtin_convertvector(v, bf16x2_t); return __builtin_bit_cast(unsigned, b); }
; DI float bflo(unsigned w) { return __uint_as_float(w << 16); }
; DI float bfhi(unsigned w) { return __uint_as_float(w & 0xffff0000u); }
; DI void phase_e(const Ctx& C, int nslab, int has_post, int pl, int ps, float pw, int has_pre, int ql, int qs, int nrows,
;                 const GAS float* xsrc, const GAS float* csrc, GAS float* xdst, GAS float* cdst, bool xs16, bool xd16) {
;     ...
;             const float r = rsqrtf(wave_sum(ss) * (1.0f / 1024.0f) + EPS);
;             if (isx && xd16) { GAS bf16* d16 = (GAS bf16*)xdst + (size_t)row * 1024;
; #pragma unroll
;                 for (int j = 0; j < 4; ++j) { v[j] += pw * gt[j] * ((y[j] * r) * gpo[j]); u32x2 w; w.x = pk2(v[j][0], v[j][1]); w.y = pk2(v[j][2], v[j][3]); __builtin_nontemporal_store(w, (GAS u32x2*)(d16 + 256 * j + 4 * lane));
;                     v[j] = (f32x4){bflo(w.x), bfhi(w.x), bflo(w.y), bfhi(w.y)}; }
.LBB0_2220:
	s_andn2_b64 vcc, exec, s[10:11]
	s_cbranch_vccnz .LBB0_2209_u0
	v_mov_b32_e32 v130, v187
	v_mov_b32_e32 v131, v189
	v_mov_b32_e32 v187, v188
	v_pk_mul_f32 v[130:131], v[130:131], v[190:191] op_sel_hi:[1,0]
	v_pk_mul_f32 v[132:133], v[186:187], v[190:191] op_sel_hi:[1,0]
	v_pk_mul_f32 v[130:131], v[4:5], v[130:131]
	v_pk_mul_f32 v[132:133], v[2:3], v[132:133]
	s_lshl_b64 s[8:9], s[6:7], 11
	s_waitcnt vmcnt(11)
	v_pk_fma_f32 v[64:65], v[100:101], v[130:131], v[64:65]
	v_pk_fma_f32 v[62:63], v[98:99], v[132:133], v[62:63]
	v_lshl_add_u64 v[142:143], v[160:161], 0, s[8:9]
	v_cvt_pk_bf16_f32 v62, v62, v63
	v_cvt_pk_bf16_f32 v63, v64, v65
	global_store_dwordx2 v[142:143], v[62:63], off
	v_lshlrev_b32_e32 v130, 16, v62
	v_and_b32_e32 v131, 0xffff0000, v62
	v_lshlrev_b32_e32 v132, 16, v63
	v_and_b32_e32 v133, 0xffff0000, v63
	v_mov_b32_e32 v62, v183
	v_mov_b32_e32 v63, v185
	v_mov_b32_e32 v183, v184
	v_pk_mul_f32 v[62:63], v[62:63], v[190:191] op_sel_hi:[1,0]
	v_pk_mul_f32 v[64:65], v[182:183], v[190:191] op_sel_hi:[1,0]
	v_pk_mul_f32 v[62:63], v[8:9], v[62:63]
	v_pk_mul_f32 v[64:65], v[6:7], v[64:65]
	s_waitcnt vmcnt(8)
	v_pk_fma_f32 v[60:61], v[104:105], v[62:63], v[60:61]
	v_pk_fma_f32 v[58:59], v[102:103], v[64:65], v[58:59]
	s_nop 0
	v_cvt_pk_bf16_f32 v58, v58, v59
	v_cvt_pk_bf16_f32 v59, v60, v61
	global_store_dwordx2 v[142:143], v[58:59], off offset:512
	v_lshlrev_b32_e32 v134, 16, v58
	v_and_b32_e32 v135, 0xffff0000, v58
	v_lshlrev_b32_e32 v136, 16, v59
	v_and_b32_e32 v137, 0xffff0000, v59
	v_pk_mul_f32 v[58:59], v[178:179], v[190:191] op_sel_hi:[1,0]
	v_pk_mul_f32 v[60:61], v[180:181], v[190:191] op_sel_hi:[1,0]
	v_pk_mul_f32 v[58:59], v[18:19], v[58:59]
	v_pk_mul_f32 v[60:61], v[20:21], v[60:61]
	s_waitcnt vmcnt(8)
	v_pk_fma_f32 v[54:55], v[106:107], v[58:59], v[54:55]
	v_pk_fma_f32 v[56:57], v[108:109], v[60:61], v[56:57]
	v_cvt_pk_bf16_f32 v54, v54, v55
	v_cvt_pk_bf16_f32 v55, v56, v57
	global_store_dwordx2 v[142:143], v[54:55], off offset:1024
	v_lshlrev_b32_e32 v138, 16, v54
	v_and_b32_e32 v139, 0xffff0000, v54
	v_lshlrev_b32_e32 v140, 16, v55
	v_and_b32_e32 v141, 0xffff0000, v55
	v_pk_mul_f32 v[54:55], v[176:177], v[190:191] op_sel_hi:[1,0]
	v_pk_mul_f32 v[56:57], v[174:175], v[190:191] op_sel_hi:[1,0]
	v_pk_mul_f32 v[54:55], v[24:25], v[54:55]
	v_pk_mul_f32 v[56:57], v[22:23], v[56:57]
	s_waitcnt vmcnt(7)
	v_pk_fma_f32 v[52:53], v[112:113], v[54:55], v[52:53]
	v_pk_fma_f32 v[50:51], v[110:111], v[56:57], v[50:51]
	s_nop 0
	v_cvt_pk_bf16_f32 v50, v50, v51
	v_cvt_pk_bf16_f32 v51, v52, v53
	global_store_dwordx2 v[142:143], v[50:51], off offset:1536
	v_lshlrev_b32_e32 v142, 16, v50
	v_and_b32_e32 v143, 0xffff0000, v50
	v_lshlrev_b32_e32 v144, 16, v51
	v_and_b32_e32 v145, 0xffff0000, v51
	s_branch .LBB0_2209_u0

; #define GAS __attribute__((address_space(1)))
; DI unsigned pk2(float lo, float hi) { f32x2_t v = {lo, hi}; bf16x2_t b = __builtin_convertvector(v, bf16x2_t); return __builtin_bit_cast(unsigned, b); }
; DI float bflo(unsigned w) { return __uint_as_float(w << 16); }
; DI float bfhi(unsigned w) { return __uint_as_float(w & 0xffff0000u); }
; DI void phase_e(const Ctx& C, int nslab, int has_post, int pl, int ps, float pw, int has_pre, int ql, int qs, int nrows,
;                 const GAS float* xsrc, const GAS float* csrc, GAS float* xdst, GAS float* cdst, bool xs16, bool xd16) {
;     ...
;             const float r = rsqrtf(wave_sum(ss) * (1.0f / 1024.0f) + EPS);
;             if (isx && xd16) { GAS bf16* d16 = (GAS bf16*)xdst + (size_t)row * 1024;
; #pragma unroll
;                 for (int j = 0; j < 4; ++j) { v[j] += pw * gt[j] * ((y[j] * r) * gpo[j]); u32x2 w; w.x = pk2(v[j][0], v[j][1]); w.y = pk2(v[j][2], v[j][3]); __builtin_nontemporal_store(w, (GAS u32x2*)(d16 + 256 * j + 4 * lane));
;                     v[j] = (f32x4){bflo(w.x), bfhi(w.x), bflo(w.y), bfhi(w.y)}; }
.Lrow1_2220:
	s_andn2_b64 vcc, exec, s[10:11]
	s_cbranch_vccnz .Lrow1_2209
	v_mov_b32_e32 v130, v187
	v_mov_b32_e32 v131, v189
	v_mov_b32_e32 v187, v188
	v_pk_mul_f32 v[130:131], v[130:131], v[190:191] op_sel_hi:[1,0]
	v_pk_mul_f32 v[132:133], v[186:187], v[190:191] op_sel_hi:[1,0]
	v_pk_mul_f32 v[130:131], v[4:5], v[130:131]
	v_pk_mul_f32 v[132:133], v[2:3], v[132:133]
	s_lshl_b64 s[8:9], s[6:7], 11
	s_waitcnt vmcnt(11)
	v_pk_fma_f32 v[36:37], v[100:101], v[130:131], v[36:37]
	v_pk_fma_f32 v[34:35], v[98:99], v[132:133], v[34:35]
	v_lshl_add_u64 v[142:143], v[160:161], 0, s[8:9]
	v_cvt_pk_bf16_f32 v34, v34, v35
	v_cvt_pk_bf16_f32 v35, v36, v37
	global_store_dwordx2 v[142:143], v[34:35], off
	v_lshlrev_b32_e32 v130, 16, v34
	v_and_b32_e32 v131, 0xffff0000, v34
	v_lshlrev_b32_e32 v132, 16, v35
	v_and_b32_e32 v133, 0xffff0000, v35
	v_mov_b32_e32 v34, v183
	v_mov_b32_e32 v35, v185
	v_mov_b32_e32 v183, v184
	v_pk_mul_f32 v[34:35], v[34:35], v[190:191] op_sel_hi:[1,0]
	v_pk_mul_f32 v[36:37], v[182:183], v[190:191] op_sel_hi:[1,0]
	v_pk_mul_f32 v[34:35], v[8:9], v[34:35]
	v_pk_mul_f32 v[36:37], v[6:7], v[36:37]
	s_waitcnt vmcnt(8)
	v_pk_fma_f32 v[40:41], v[104:105], v[34:35], v[40:41]
	v_pk_fma_f32 v[38:39], v[102:103], v[36:37], v[38:39]
	s_nop 0
	v_cvt_pk_bf16_f32 v38, v38, v39
	v_cvt_pk_bf16_f32 v39, v40, v41
	global_store_dwordx2 v[142:143], v[38:39], off offset:512
	v_lshlrev_b32_e32 v134, 16, v38
	v_and_b32_e32 v135, 0xffff0000, v38
	v_lshlrev_b32_e32 v136, 16, v39
	v_and_b32_e32 v137, 0xffff0000, v39
	v_pk_mul_f32 v[38:39], v[178:179], v[190:191] op_sel_hi:[1,0]
	v_pk_mul_f32 v[40:41], v[180:181], v[190:191] op_sel_hi:[1,0]
	v_pk_mul_f32 v[38:39], v[18:19], v[38:39]
	v_pk_mul_f32 v[40:41], v[20:21], v[40:41]
	s_waitcnt vmcnt(8)
	v_pk_fma_f32 v[42:43], v[106:107], v[38:39], v[42:43]
	v_pk_fma_f32 v[44:45], v[108:109], v[40:41], v[44:45]
	v_cvt_pk_bf16_f32 v42, v42, v43
	v_cvt_pk_bf16_f32 v43, v44, v45
	global_store_dwordx2 v[142:143], v[42:43], off offset:1024
	v_lshlrev_b32_e32 v138, 16, v42
	v_and_b32_e32 v139, 0xffff0000, v42
	v_lshlrev_b32_e32 v140, 16, v43
	v_and_b32_e32 v141, 0xffff0000, v43
	v_pk_mul_f32 v[42:43], v[176:177], v[190:191] op_sel_hi:[1,0]
	v_pk_mul_f32 v[44:45], v[174:175], v[190:191] op_sel_hi:[1,0]
	v_pk_mul_f32 v[42:43], v[24:25], v[42:43]
	v_pk_mul_f32 v[44:45], v[22:23], v[44:45]
	s_waitcnt vmcnt(7)
	v_pk_fma_f32 v[48:49], v[112:113], v[42:43], v[48:49]
	v_pk_fma_f32 v[46:47], v[110:111], v[44:45], v[46:47]
	s_nop 0
	v_cvt_pk_bf16_f32 v46, v46, v47
	v_cvt_pk_bf16_f32 v47, v48, v49
	global_store_dwordx2 v[142:143], v[46:47], off offset:1536
	v_lshlrev_b32_e32 v142, 16, v46
	v_and_b32_e32 v143, 0xffff0000, v46
	v_lshlrev_b32_e32 v144, 16, v47
	v_and_b32_e32 v145, 0xffff0000, v47
	s_branch .Lrow1_2209

; #define GAS __attribute__((address_space(1)))
; DI unsigned pk2(float lo, float hi) { f32x2_t v = {lo, hi}; bf16x2_t b = __builtin_convertvector(v, bf16x2_t); return __builtin_bit_cast(unsigned, b); }
; DI float bflo(unsigned w) { return __uint_as_float(w << 16); }
; DI float bfhi(unsigned w) { return __uint_as_float(w & 0xffff0000u); }
; DI void phase_e(const Ctx& C, int nslab, int has_post, int pl, int ps, float pw, int has_pre, int ql, int qs, int nrows,
;                 const GAS float* xsrc, const GAS float* csrc, GAS float* xdst, GAS float* cdst, bool xs16, bool xd16) {
;     ...
;             const float r = rsqrtf(wave_sum(ss) * (1.0f / 1024.0f) + EPS);
;             if (isx && xd16) { GAS bf16* d16 = (GAS bf16*)xdst + (size_t)row * 1024;
; #pragma unroll
;                 for (int j = 0; j < 4; ++j) { v[j] += pw * gt[j] * ((y[j] * r) * gpo[j]); u32x2 w; w.x = pk2(v[j][0], v[j][1]); w.y = pk2(v[j][2], v[j][3]); __builtin_nontemporal_store(w, (GAS u32x2*)(d16 + 256 * j + 4 * lane));
;                     v[j] = (f32x4){bflo(w.x), bfhi(w.x), bflo(w.y), bfhi(w.y)}; }
.Lrow2_2220:
	s_andn2_b64 vcc, exec, s[10:11]
	s_cbranch_vccnz .LBB0_2209
	v_mov_b32_e32 v130, v187
	v_mov_b32_e32 v131, v189
	v_mov_b32_e32 v187, v188
	v_pk_mul_f32 v[130:131], v[130:131], v[190:191] op_sel_hi:[1,0]
	v_pk_mul_f32 v[132:133], v[186:187], v[190:191] op_sel_hi:[1,0]
	v_pk_mul_f32 v[130:131], v[4:5], v[130:131]
	v_pk_mul_f32 v[132:133], v[2:3], v[132:133]
	s_lshl_b64 s[8:9], s[6:7], 11
	s_waitcnt vmcnt(11)
	v_pk_fma_f32 v[116:117], v[100:101], v[130:131], v[116:117]
	v_pk_fma_f32 v[114:115], v[98:99], v[132:133], v[114:115]
	v_lshl_add_u64 v[142:143], v[160:161], 0, s[8:9]
	v_cvt_pk_bf16_f32 v114, v114, v115
	v_cvt_pk_bf16_f32 v115, v116, v117
	global_store_dwordx2 v[142:143], v[114:115], off
	v_lshlrev_b32_e32 v130, 16, v114
	v_and_b32_e32 v131, 0xffff0000, v114
	v_lshlrev_b32_e32 v132, 16, v115
	v_and_b32_e32 v133, 0xffff0000, v115
	v_mov_b32_e32 v114, v183
	v_mov_b32_e32 v115, v185
	v_mov_b32_e32 v183, v184
	v_pk_mul_f32 v[114:115], v[114:115], v[190:191] op_sel_hi:[1,0]
	v_pk_mul_f32 v[116:117], v[182:183], v[190:191] op_sel_hi:[1,0]
	v_pk_mul_f32 v[114:115], v[8:9], v[114:115]
	v_pk_mul_f32 v[116:117], v[6:7], v[116:117]
	s_waitcnt vmcnt(8)
	v_pk_fma_f32 v[120:121], v[104:105], v[114:115], v[120:121]
	v_pk_fma_f32 v[118:119], v[102:103], v[116:117], v[118:119]
	s_nop 0
	v_cvt_pk_bf16_f32 v118, v118, v119
	v_cvt_pk_bf16_f32 v119, v120, v121
	global_store_dwordx2 v[142:143], v[118:119], off offset:512
	v_lshlrev_b32_e32 v134, 16, v118
	v_and_b32_e32 v135, 0xffff0000, v118
	v_lshlrev_b32_e32 v136, 16, v119
	v_and_b32_e32 v137, 0xffff0000, v119
	v_pk_mul_f32 v[118:119], v[178:179], v[190:191] op_sel_hi:[1,0]
	v_pk_mul_f32 v[120:121], v[180:181], v[190:191] op_sel_hi:[1,0]
	v_pk_mul_f32 v[118:119], v[18:19], v[118:119]
	v_pk_mul_f32 v[120:121], v[20:21], v[120:121]
	s_waitcnt vmcnt(8)
	v_pk_fma_f32 v[122:123], v[106:107], v[118:119], v[122:123]
	v_pk_fma_f32 v[124:125], v[108:109], v[120:121], v[124:125]
	v_cvt_pk_bf16_f32 v122, v122, v123
	v_cvt_pk_bf16_f32 v123, v124, v125
	global_store_dwordx2 v[142:143], v[122:123], off offset:1024
	v_lshlrev_b32_e32 v138, 16, v122
	v_and_b32_e32 v139, 0xffff0000, v122
	v_lshlrev_b32_e32 v140, 16, v123
	v_and_b32_e32 v141, 0xffff0000, v123
	v_pk_mul_f32 v[122:123], v[176:177], v[190:191] op_sel_hi:[1,0]
	v_pk_mul_f32 v[124:125], v[174:175], v[190:191] op_sel_hi:[1,0]
	v_pk_mul_f32 v[122:123], v[24:25], v[122:123]
	v_pk_mul_f32 v[124:125], v[22:23], v[124:125]
	s_waitcnt vmcnt(7)
	v_pk_fma_f32 v[128:129], v[112:113], v[122:123], v[128:129]
	v_pk_fma_f32 v[126:127], v[110:111], v[124:125], v[126:127]
	s_nop 0
	v_cvt_pk_bf16_f32 v126, v126, v127
	v_cvt_pk_bf16_f32 v127, v128, v129
	global_store_dwordx2 v[142:143], v[126:127], off offset:1536
	v_lshlrev_b32_e32 v142, 16, v126
	v_and_b32_e32 v143, 0xffff0000, v126
	v_lshlrev_b32_e32 v144, 16, v127
	v_and_b32_e32 v145, 0xffff0000, v127
	s_branch .LBB0_2209
